# v36 plus 8-byte code placement shift ahead of the attention phase (two s_nop outside loops)
# speedup vs baseline: 1.0375x; 1.0021x over previous
; DI void attn_phase(int layer, const Params& P, char* lds) {
;   const int NITEMS = layer + 1 < DEPTH ? 4096 + 64 : 4096;
;   for (int w = blockIdx.x; w < NITEMS; w += gridDim.x) {
;     if (w < 1024) attn_item<64, 128, 0>(layer, w >> 3, w & 7, lds, P);
;     else if (w < 2048) attn_item<192, 128, 1>(layer, (w - 1024) >> 3, w & 7, lds, P);
;     else if (w < 4096) attn_item<64, 64, 2>(layer, (w - 2048) >> 4, w & 15, lds, P);
;     else if (w < 4112) attn_item<64, 128, 0>(layer, 128 + ((w - 4096) >> 3), w & 7, lds, P);
;     else if (w < 4128) attn_item<192, 128, 1>(layer, 128 + ((w - 4112) >> 3), w & 7, lds, P);
;     else attn_item<64, 64, 2>(layer, 128 + ((w - 4128) >> 4), w & 15, lds, P);
;   }
; __global__ void __launch_bounds__(256, 2) fwd_megakernel(Params P) {
;     ...
;     else if (kind == 4) attn_phase(layer, P, lds);
.LBB0_292:
	s_nop 0
	s_nop 0
	s_andn2_b64 vcc, exec, s[0:1]
	s_cbranch_vccnz .LBB0_385
	s_cmp_eq_u32 s60, 0
	s_movk_i32 s0, 0x1040
	s_cselect_b32 s22, s0, 0x1000
	s_cmp_ge_i32 s53, s22
	s_cbranch_scc1 .LBB0_385
	v_writelane_b32 v255, s58, 25
	s_mov_b32 s61, s35
	v_writelane_b32 v255, s57, 28
	s_lshl_b32 s23, s60, 4
	s_lshl_b64 s[40:41], s[60:61], 2
	v_readlane_b32 s0, v252, 2
	v_writelane_b32 v255, s56, 27
	v_readlane_b32 s1, v252, 3
	s_add_u32 s42, s0, s40
	s_mov_b32 s0, s60
	s_addc_u32 s43, s1, s41
	v_writelane_b32 v255, s0, 23
	s_lshl_b32 s34, s60, 7
	v_readlane_b32 s56, v254, 19
	v_writelane_b32 v255, s1, 24
	s_lshl_b64 s[0:1], s[34:35], 2
	v_readlane_b32 s62, v254, 25
	v_readlane_b32 s57, v254, 20
	v_readlane_b32 s63, v254, 26
	s_add_u32 s56, s62, s0
	s_addc_u32 s57, s63, s1
	v_readlane_b32 s24, v253, 50
	v_readlane_b32 s25, v253, 48
	s_mov_b32 s28, s53
	s_mov_b32 s29, s53
	s_mov_b64 s[96:97], s[56:57]
	v_readlane_b32 s58, v254, 21
	v_readlane_b32 s59, v254, 22
	v_readlane_b32 s60, v254, 23
	v_readlane_b32 s61, v254, 24
	v_readlane_b32 s64, v254, 27
	v_readlane_b32 s65, v254, 28
	v_readlane_b32 s66, v254, 29
	v_readlane_b32 s67, v254, 30
	v_readlane_b32 s68, v254, 31
	v_readlane_b32 s69, v254, 32
	v_readlane_b32 s70, v254, 33
	v_readlane_b32 s71, v254, 34
	s_branch .LBB0_297
